# barrier 1 narrowed by dependency: phase-1 job remap co-locates each row panel's producers with its phase-2 consumers (same XCD), panel arrival word + weights-ready count gate phase 2, grid barrier 1 c
# speedup vs baseline: 1.0285x; 1.0025x over previous
; __device__ __forceinline__ unsigned cvt_pk_bf16(float lo, float hi) { unsigned r; asm volatile("v_cvt_pk_bf16_f32 %0, %1, %2" : "=v"(r) : "v"(lo), "v"(hi)); return r; }
; __device__ void phase0(const Params& p, LAS unsigned char* lds) {
;     ...
;         const int r0 = tid >> 4, c4 = (tid & 15) * 4;
;         int job = blockIdx.x;
;         f32x4 va, vb;
;         { const int kt = job & 15, ntile = job >> 4; const int n0 = ntile * 64, k0 = kt * 64; const int c0 = n0 < 5120 ? n0 : n0 + 16;
;           va = __builtin_nontemporal_load((const f32x4*)(p.in_w + (size_t)(k0 + r0) * 8208 + c0 + c4)); vb = __builtin_nontemporal_load((const f32x4*)(p.in_w + (size_t)(k0 + r0 + 32) * 8208 + c0 + c4)); }
;         for (; job < 2048; job += gridDim.x) {
;             const int kt = job & 15, ntile = job >> 4; const int n0 = ntile * 64, k0 = kt * 64;
;             T[r0 * 65 + c4] = va[0]; T[r0 * 65 + c4 + 1] = va[1]; T[r0 * 65 + c4 + 2] = va[2]; T[r0 * 65 + c4 + 3] = va[3];
;             T[(r0 + 32) * 65 + c4] = vb[0]; T[(r0 + 32) * 65 + c4 + 1] = vb[1]; T[(r0 + 32) * 65 + c4 + 2] = vb[2]; T[(r0 + 32) * 65 + c4 + 3] = vb[3];
;             __syncthreads();
;             const int nj = job + gridDim.x;
;             if (nj < 2048) { const int kt2 = nj & 15, nt2 = nj >> 4; const int n2 = nt2 * 64, k2 = kt2 * 64; const int c2 = n2 < 5120 ? n2 : n2 + 16;
;                 va = __builtin_nontemporal_load((const f32x4*)(p.in_w + (size_t)(k2 + r0) * 8208 + c2 + c4)); vb = __builtin_nontemporal_load((const f32x4*)(p.in_w + (size_t)(k2 + r0 + 32) * 8208 + c2 + c4)); }
;             { const int n = tid >> 3, kc = (tid & 7) * 8; float f[8];
; #pragma unroll
;               for (int j = 0; j < 8; ++j) f[j] = T[(kc + j) * 65 + n];
;               u32x4 w; w.x = cvt_pk_bf16(f[0], f[1]); w.y = cvt_pk_bf16(f[2], f[3]); w.z = cvt_pk_bf16(f[4], f[5]); w.w = cvt_pk_bf16(f[6], f[7]);
;               *(u32x4*)(WinT + (size_t)(n0 + n) * 1024 + k0 + kc) = w; }
;             __syncthreads();
;         }
.LBB0_70:
	s_or_b64 exec, exec, s[4:5]
	s_add_u32 s20, s70, 0x2400000
	s_addc_u32 s21, s71, 0
	v_ashrrev_i32_e32 v14, 4, v224
	s_lshl_b32 s4, s2, 6
	s_and_b32 s3, s4, 0x3c0
	v_add_u32_e32 v2, s3, v14
	s_mov_b32 s5, 0x8040
	v_mul_lo_u32 v0, v2, s5
	v_lshlrev_b32_e32 v20, 2, v224
	v_and_b32_e32 v20, 60, v20
	v_lshl_add_u32 v30, v20, 2, v0
	v_add_u32_e32 v31, 0x100800, v30
	s_lshr_b32 s5, s2, 4
	s_lshl_b32 s5, s5, 8
	s_add_u32 s6, s50, s5
	s_addc_u32 s7, s51, 0
	global_load_dwordx4 v[128:131], v30, s[6:7] nt
	global_load_dwordx4 v[132:135], v31, s[6:7] nt
	s_add_u32 s6, s6, 4096
	s_addc_u32 s7, s7, 0
	global_load_dwordx4 v[136:139], v30, s[6:7] nt
	global_load_dwordx4 v[140:143], v31, s[6:7] nt
	s_add_u32 s6, s6, 4096
	s_addc_u32 s7, s7, 0
	global_load_dwordx4 v[144:147], v30, s[6:7] nt
	global_load_dwordx4 v[148:151], v31, s[6:7] nt
	s_add_u32 s6, s6, 4096
	s_addc_u32 s7, s7, 0
	global_load_dwordx4 v[152:155], v30, s[6:7] nt
	global_load_dwordx4 v[156:159], v31, s[6:7] nt
	s_add_u32 s6, s6, 4096
	s_addc_u32 s7, s7, 0
	global_load_dwordx4 v[160:163], v30, s[6:7] nt
	global_load_dwordx4 v[164:167], v31, s[6:7] nt
	s_add_u32 s6, s6, 4160
	s_addc_u32 s7, s7, 0
	global_load_dwordx4 v[168:171], v30, s[6:7] nt
	global_load_dwordx4 v[172:175], v31, s[6:7] nt
	s_add_u32 s6, s6, 4096
	s_addc_u32 s7, s7, 0
	global_load_dwordx4 v[176:179], v30, s[6:7] nt
	global_load_dwordx4 v[180:183], v31, s[6:7] nt
	s_add_u32 s6, s6, 4096
	s_addc_u32 s7, s7, 0
	global_load_dwordx4 v[184:187], v30, s[6:7] nt
	global_load_dwordx4 v[188:191], v31, s[6:7] nt
	v_ashrrev_i32_e32 v16, 3, v224
	v_lshlrev_b32_e32 v9, 3, v224
	v_and_b32_e32 v9, 56, v9
	s_movk_i32 s8, 0x104
	v_mul_lo_u32 v10, v14, s8
	v_lshl_add_u32 v15, v20, 2, v10
	v_add_u32_e32 v17, 0x2080, v15
	v_mul_u32_u24_e32 v21, 0x104, v9
	v_lshl_add_u32 v19, v16, 2, v21
	v_add_u32_e32 v18, 0x400, v19
	v_lshlrev_b32_e32 v12, 11, v16
	v_lshl_add_u32 v12, v9, 1, v12
	s_lshr_b32 s8, s2, 4
	s_lshl_b32 s8, s8, 17
	s_lshl_b32 s9, s3, 1
	s_add_u32 s8, s8, s9
	s_add_u32 s8, s20, s8
	s_addc_u32 s9, s21, 0
	s_waitcnt vmcnt(14)
	ds_write2_b32 v15, v128, v129 offset1:1
	ds_write2_b32 v15, v130, v131 offset0:2 offset1:3
	ds_write2_b32 v17, v132, v133 offset1:1
	ds_write2_b32 v17, v134, v135 offset0:2 offset1:3
	s_waitcnt lgkmcnt(0)
	s_barrier
	ds_read2_b32 v[0:1], v19 offset1:65
	ds_read2_b32 v[2:3], v19 offset0:130 offset1:195
	ds_read2_b32 v[4:5], v18 offset0:4 offset1:69
	ds_read2_b32 v[6:7], v18 offset0:134 offset1:199
	s_waitcnt lgkmcnt(0)
	v_cvt_pk_bf16_f32 v22, v0, v1
	v_cvt_pk_bf16_f32 v23, v2, v3
	v_cvt_pk_bf16_f32 v24, v4, v5
	v_cvt_pk_bf16_f32 v25, v6, v7
	global_store_dwordx4 v12, v[22:25], s[8:9] sc1
	s_waitcnt vmcnt(13)
	v_add_u32_e32 v26, 0x4200, v15
	v_add_u32_e32 v27, 0x4200, v17
	v_add_u32_e32 v28, 0x4200, v19
	v_add_u32_e32 v29, 0x4200, v18
	ds_write2_b32 v26, v136, v137 offset1:1
	ds_write2_b32 v26, v138, v139 offset0:2 offset1:3
	ds_write2_b32 v27, v140, v141 offset1:1
	ds_write2_b32 v27, v142, v143 offset0:2 offset1:3
	s_waitcnt lgkmcnt(0)
	s_barrier
	ds_read2_b32 v[0:1], v28 offset1:65
	ds_read2_b32 v[2:3], v28 offset0:130 offset1:195
	ds_read2_b32 v[4:5], v29 offset0:4 offset1:69
	ds_read2_b32 v[6:7], v29 offset0:134 offset1:199
	s_add_u32 s8, s8, 0x200000
	s_addc_u32 s9, s9, 0
	s_waitcnt lgkmcnt(0)
	v_cvt_pk_bf16_f32 v22, v0, v1
	v_cvt_pk_bf16_f32 v23, v2, v3
	v_cvt_pk_bf16_f32 v24, v4, v5
	v_cvt_pk_bf16_f32 v25, v6, v7
	global_store_dwordx4 v12, v[22:25], s[8:9] sc1
	s_waitcnt vmcnt(12)
	ds_write2_b32 v15, v144, v145 offset1:1
	ds_write2_b32 v15, v146, v147 offset0:2 offset1:3
	ds_write2_b32 v17, v148, v149 offset1:1
	ds_write2_b32 v17, v150, v151 offset0:2 offset1:3
	s_waitcnt lgkmcnt(0)
	s_barrier
; __device__ __forceinline__ unsigned cvt_pk_bf16(float lo, float hi) { unsigned r; asm volatile("v_cvt_pk_bf16_f32 %0, %1, %2" : "=v"(r) : "v"(lo), "v"(hi)); return r; }
; __device__ void phase0(const Params& p, LAS unsigned char* lds) {
;     ...
;         for (; job < 2048; job += gridDim.x) {
;             const int kt = job & 15, ntile = job >> 4; const int n0 = ntile * 64, k0 = kt * 64;
;             T[r0 * 65 + c4] = va[0]; T[r0 * 65 + c4 + 1] = va[1]; T[r0 * 65 + c4 + 2] = va[2]; T[r0 * 65 + c4 + 3] = va[3];
;             T[(r0 + 32) * 65 + c4] = vb[0]; T[(r0 + 32) * 65 + c4 + 1] = vb[1]; T[(r0 + 32) * 65 + c4 + 2] = vb[2]; T[(r0 + 32) * 65 + c4 + 3] = vb[3];
;             __syncthreads();
;             const int nj = job + gridDim.x;
;             if (nj < 2048) { const int kt2 = nj & 15, nt2 = nj >> 4; const int n2 = nt2 * 64, k2 = kt2 * 64; const int c2 = n2 < 5120 ? n2 : n2 + 16;
;                 va = __builtin_nontemporal_load((const f32x4*)(p.in_w + (size_t)(k2 + r0) * 8208 + c2 + c4)); vb = __builtin_nontemporal_load((const f32x4*)(p.in_w + (size_t)(k2 + r0 + 32) * 8208 + c2 + c4)); }
;             { const int n = tid >> 3, kc = (tid & 7) * 8; float f[8];
; #pragma unroll
;               for (int j = 0; j < 8; ++j) f[j] = T[(kc + j) * 65 + n];
;               u32x4 w; w.x = cvt_pk_bf16(f[0], f[1]); w.y = cvt_pk_bf16(f[2], f[3]); w.z = cvt_pk_bf16(f[4], f[5]); w.w = cvt_pk_bf16(f[6], f[7]);
;               *(u32x4*)(WinT + (size_t)(n0 + n) * 1024 + k0 + kc) = w; }
;             __syncthreads();
;         }
	ds_read2_b32 v[0:1], v19 offset1:65
	ds_read2_b32 v[2:3], v19 offset0:130 offset1:195
	ds_read2_b32 v[4:5], v18 offset0:4 offset1:69
	ds_read2_b32 v[6:7], v18 offset0:134 offset1:199
	s_add_u32 s8, s8, 0x200000
	s_addc_u32 s9, s9, 0
	s_waitcnt lgkmcnt(0)
	v_cvt_pk_bf16_f32 v22, v0, v1
	v_cvt_pk_bf16_f32 v23, v2, v3
	v_cvt_pk_bf16_f32 v24, v4, v5
	v_cvt_pk_bf16_f32 v25, v6, v7
	global_store_dwordx4 v12, v[22:25], s[8:9] sc1
	s_waitcnt vmcnt(11)
	ds_write2_b32 v26, v152, v153 offset1:1
	ds_write2_b32 v26, v154, v155 offset0:2 offset1:3
	ds_write2_b32 v27, v156, v157 offset1:1
	ds_write2_b32 v27, v158, v159 offset0:2 offset1:3
	s_waitcnt lgkmcnt(0)
	s_barrier
	ds_read2_b32 v[0:1], v28 offset1:65
	ds_read2_b32 v[2:3], v28 offset0:130 offset1:195
	ds_read2_b32 v[4:5], v29 offset0:4 offset1:69
	ds_read2_b32 v[6:7], v29 offset0:134 offset1:199
	s_add_u32 s8, s8, 0x200000
	s_addc_u32 s9, s9, 0
	s_waitcnt lgkmcnt(0)
	v_cvt_pk_bf16_f32 v22, v0, v1
	v_cvt_pk_bf16_f32 v23, v2, v3
	v_cvt_pk_bf16_f32 v24, v4, v5
	v_cvt_pk_bf16_f32 v25, v6, v7
	global_store_dwordx4 v12, v[22:25], s[8:9] sc1
	s_waitcnt vmcnt(10)
	ds_write2_b32 v15, v160, v161 offset1:1
	ds_write2_b32 v15, v162, v163 offset0:2 offset1:3
	ds_write2_b32 v17, v164, v165 offset1:1
	ds_write2_b32 v17, v166, v167 offset0:2 offset1:3
	s_waitcnt lgkmcnt(0)
	s_barrier
	ds_read2_b32 v[0:1], v19 offset1:65
	ds_read2_b32 v[2:3], v19 offset0:130 offset1:195
	ds_read2_b32 v[4:5], v18 offset0:4 offset1:69
	ds_read2_b32 v[6:7], v18 offset0:134 offset1:199
	s_add_u32 s8, s8, 0x200000
	s_addc_u32 s9, s9, 0
	s_waitcnt lgkmcnt(0)
	v_cvt_pk_bf16_f32 v22, v0, v1
	v_cvt_pk_bf16_f32 v23, v2, v3
	v_cvt_pk_bf16_f32 v24, v4, v5
	v_cvt_pk_bf16_f32 v25, v6, v7
	global_store_dwordx4 v12, v[22:25], s[8:9] sc1
	s_waitcnt vmcnt(9)
	ds_write2_b32 v26, v168, v169 offset1:1
	ds_write2_b32 v26, v170, v171 offset0:2 offset1:3
	ds_write2_b32 v27, v172, v173 offset1:1
	ds_write2_b32 v27, v174, v175 offset0:2 offset1:3
	s_waitcnt lgkmcnt(0)
	s_barrier
	ds_read2_b32 v[0:1], v28 offset1:65
	ds_read2_b32 v[2:3], v28 offset0:130 offset1:195
	ds_read2_b32 v[4:5], v29 offset0:4 offset1:69
	ds_read2_b32 v[6:7], v29 offset0:134 offset1:199
	s_add_u32 s8, s8, 0x200000
	s_addc_u32 s9, s9, 0
	s_waitcnt lgkmcnt(0)
	v_cvt_pk_bf16_f32 v22, v0, v1
	v_cvt_pk_bf16_f32 v23, v2, v3
	v_cvt_pk_bf16_f32 v24, v4, v5
	v_cvt_pk_bf16_f32 v25, v6, v7
	global_store_dwordx4 v12, v[22:25], s[8:9] sc1
	s_waitcnt vmcnt(8)
	ds_write2_b32 v15, v176, v177 offset1:1
	ds_write2_b32 v15, v178, v179 offset0:2 offset1:3
	ds_write2_b32 v17, v180, v181 offset1:1
	ds_write2_b32 v17, v182, v183 offset0:2 offset1:3
	s_waitcnt lgkmcnt(0)
	s_barrier
	ds_read2_b32 v[0:1], v19 offset1:65
	ds_read2_b32 v[2:3], v19 offset0:130 offset1:195
	ds_read2_b32 v[4:5], v18 offset0:4 offset1:69
	ds_read2_b32 v[6:7], v18 offset0:134 offset1:199
	s_add_u32 s8, s8, 0x200000
	s_addc_u32 s9, s9, 0
	s_waitcnt lgkmcnt(0)
	v_cvt_pk_bf16_f32 v22, v0, v1
	v_cvt_pk_bf16_f32 v23, v2, v3
	v_cvt_pk_bf16_f32 v24, v4, v5
	v_cvt_pk_bf16_f32 v25, v6, v7
	global_store_dwordx4 v12, v[22:25], s[8:9] sc1
	s_waitcnt vmcnt(7)
	ds_write2_b32 v26, v184, v185 offset1:1
	ds_write2_b32 v26, v186, v187 offset0:2 offset1:3
	ds_write2_b32 v27, v188, v189 offset1:1
	ds_write2_b32 v27, v190, v191 offset0:2 offset1:3
	s_waitcnt lgkmcnt(0)
	s_barrier
	ds_read2_b32 v[0:1], v28 offset1:65
	ds_read2_b32 v[2:3], v28 offset0:130 offset1:195
	ds_read2_b32 v[4:5], v29 offset0:4 offset1:69
	ds_read2_b32 v[6:7], v29 offset0:134 offset1:199
	s_add_u32 s8, s8, 0x200000
	s_addc_u32 s9, s9, 0
	s_waitcnt lgkmcnt(0)
	v_cvt_pk_bf16_f32 v22, v0, v1
	v_cvt_pk_bf16_f32 v23, v2, v3
	v_cvt_pk_bf16_f32 v24, v4, v5
	v_cvt_pk_bf16_f32 v25, v6, v7
	global_store_dwordx4 v12, v[22:25], s[8:9] sc1
	s_barrier
	s_waitcnt vmcnt(0)
	s_barrier
	v_cmp_eq_u32_e32 vcc, 64, v224
	s_and_saveexec_b64 s[4:5], vcc
	s_add_u32 s6, s70, 0xff83d00
	s_addc_u32 s7, s71, 0
	v_mov_b32_e32 v0, 0
	v_mov_b32_e32 v1, 1
	global_atomic_add v0, v1, s[6:7]
	s_or_b64 exec, exec, s[4:5]

; #define LAS __attribute__((address_space(3)))
; __device__ __forceinline__ int opaque_tid() { int t = (int)threadIdx.x; asm volatile("" : "+v"(t)); return t; }
; __device__ void phase1(const Params& p, LAS unsigned char* lds) {
;     const int tid = opaque_tid(), wid = tid >> 6, lane = tid & 63;
;     LAS float* gs = (LAS float*)lds; LAS float* sh = gs + 1024; LAS float* gsc = sh + 1024; LAS float* shc = gsc + 1024; LAS float* WgT = shc + 1024;
;     const float* modp = (const float*)(p.ws + OFF_MODP);
;     bf16_t* AB = (bf16_t*)(p.ws + OFF_AB);
;     if (tid < 64) {
;         unsigned spins = 0;
;         while ((unsigned)__builtin_amdgcn_readfirstlane(__hip_atomic_load((unsigned*)(p.ws + OFF_ACNT), __ATOMIC_RELAXED, __HIP_MEMORY_SCOPE_AGENT)) < gridDim.x) { __builtin_amdgcn_s_sleep(2); if (++spins > (1u << 22)) break; }
;         __builtin_amdgcn_fence(__ATOMIC_ACQUIRE, "agent"); asm volatile("s_waitcnt vmcnt(0)" ::: "memory"); }
;     __syncthreads();
;     for (int job = blockIdx.x; job < 256; job += gridDim.x) {
;         const int b = job >> 5;
;         for (int i = tid; i < 1024; i += 512) {
;             float s0 = p.ada_b[i], s1 = p.ada_b[1024 + i], s2 = p.ada_b[2048 + i], c0 = s0, c1 = s1;
; #pragma unroll
;             for (int ks = 0; ks < 8; ++ks) { const float* mp = modp + (size_t)(ks * 9 + b) * 3072; s0 += mp[i]; s1 += mp[1024 + i]; s2 += mp[2048 + i];
;                 const float* mc = modp + (size_t)(ks * 9 + 8) * 3072; c0 += mc[i]; c1 += mc[1024 + i]; }
;             const float nw = p.norm_w[i];
;             gs[i] = nw * (1.0f + s1); sh[i] = s0; gsc[i] = nw * (1.0f + c1); shc[i] = c0;
;             if ((job & 31) == 0) ((float*)(p.ws + OFF_GATEV))[b * 1024 + i] = s2;
;         }
;         for (int i = tid; i < 16384; i += 512) { const int j = i & 15, k = i >> 4; WgT[j * 1024 + k] = p.in_w[(size_t)k * 8208 + 5120 + j]; }
;         __syncthreads();
;         const int crow = job * 8 + wid; const int cb = crow >> 8;
;         float* gl = (float*)(p.ws + OFF_GL) + (size_t)b * 16 * 2048 + (size_t)lane * 2048; float* gc = (float*)(p.ws + OFF_GC) + (size_t)cb * 16 * 256 + (size_t)lane * 256 + (crow & 255);
;         const int rbase = job * 64 + wid * 8;
.LBB0_87:
	s_or_b64 exec, exec, s[4:5]
	s_load_dwordx16 s[4:19], s[0:1], 0x40
	s_andn2_b64 vcc, exec, s[24:25]
	v_mbcnt_lo_u32_b32 v158, -1, 0
	s_waitcnt lgkmcnt(0)
	s_barrier
	v_writelane_b32 v254, s4, 6
	s_nop 1
	v_writelane_b32 v254, s5, 7
	v_writelane_b32 v254, s6, 8
	v_writelane_b32 v254, s7, 9
	v_writelane_b32 v254, s8, 10
	v_writelane_b32 v254, s9, 11
	v_writelane_b32 v254, s10, 12
	v_writelane_b32 v254, s11, 13
	v_writelane_b32 v254, s12, 14
	v_writelane_b32 v254, s13, 15
	v_writelane_b32 v254, s14, 16
	v_writelane_b32 v254, s15, 17
	v_writelane_b32 v254, s16, 18
	v_writelane_b32 v254, s17, 19
	v_writelane_b32 v254, s18, 20
	v_writelane_b32 v254, s19, 21
	v_writelane_b32 v254, s20, 22
	s_nop 1
	v_writelane_b32 v254, s21, 23
	s_cbranch_vccnz .LBB0_113
	s_waitcnt vmcnt(1)
	v_mbcnt_hi_u32_b32 v4, -1, v158
	v_and_b32_e32 v7, 64, v4
	v_xor_b32_e32 v5, 32, v4
	v_add_u32_e32 v7, 64, v7
	v_cmp_lt_i32_e32 vcc, v5, v7
	v_and_b32_e32 v6, 63, v32
	v_mov_b32_e32 v35, 0
	v_cndmask_b32_e32 v5, v4, v5, vcc
	v_lshlrev_b32_e32 v53, 2, v5
	v_xor_b32_e32 v5, 16, v4
	v_cmp_lt_i32_e32 vcc, v5, v7
	v_lshlrev_b32_e32 v34, 13, v6
	v_lshlrev_b32_e32 v0, 10, v6
	v_cndmask_b32_e32 v5, v4, v5, vcc
	v_lshlrev_b32_e32 v94, 2, v5
	v_xor_b32_e32 v5, 8, v4
	v_cmp_lt_i32_e32 vcc, v5, v7
	v_mov_b32_e32 v1, v35
	s_mov_b64 s[18:19], 0xfc00000
	v_cndmask_b32_e32 v5, v4, v5, vcc
	v_lshlrev_b32_e32 v95, 2, v5
	v_xor_b32_e32 v5, 4, v4
	v_cmp_lt_i32_e32 vcc, v5, v7
	v_lshl_add_u64 v[0:1], s[70:71], 0, v[0:1]
	v_readlane_b32 s52, v254, 6
	v_cndmask_b32_e32 v5, v4, v5, vcc
	v_lshlrev_b32_e32 v96, 2, v5
	v_xor_b32_e32 v5, 2, v4
	v_cmp_lt_i32_e32 vcc, v5, v7
	s_movk_i32 s3, 0x4000
	v_lshlrev_b32_e32 v2, 2, v6
	v_cndmask_b32_e32 v5, v4, v5, vcc
	v_lshlrev_b32_e32 v97, 2, v5
	v_xor_b32_e32 v5, 1, v4
	v_cmp_lt_i32_e32 vcc, v5, v7
	v_mov_b32_e32 v3, v35
	v_readlane_b32 s53, v254, 7
	v_cndmask_b32_e32 v4, v4, v5, vcc
	v_lshlrev_b32_e32 v98, 2, v4
	v_lshlrev_b32_e32 v4, 3, v6
	v_mov_b32_e32 v5, v35
	v_lshl_add_u64 v[36:37], s[70:71], 0, v[4:5]
	v_and_b32_e32 v4, 8, v32
	v_cmp_eq_u32_e64 s[6:7], 0, v4
	v_and_b32_e32 v4, 4, v32
	v_cmp_eq_u32_e64 s[8:9], 0, v4
	v_cmp_ne_u32_e64 s[10:11], 0, v4
	v_and_b32_e32 v4, 2, v32
	v_cmp_eq_u32_e64 s[12:13], 0, v4
	v_and_b32_e32 v4, 1, v32
	v_cmp_eq_u32_e64 s[14:15], 0, v4
	v_lshl_add_u64 v[4:5], s[70:71], 0, v[34:35]
	v_lshl_add_u64 v[40:41], v[4:5], 0, s[18:19]
	s_mov_b64 s[18:19], 0xfd00000
	v_lshl_add_u64 v[42:43], v[0:1], 0, s[18:19]
	v_max_i32_e32 v0, 0x3e00, v32
	v_sub_u32_e32 v0, v0, v32
	v_add_u32_e32 v0, 0x1ff, v0
	v_lshrrev_b32_e32 v1, 9, v0
	v_cmp_gt_i32_e64 s[4:5], s3, v32
	v_lshl_add_u64 v[44:45], s[52:53], 0, v[2:3]
	s_movk_i32 s3, 0x1ff
	v_add_u32_e32 v3, 1, v1
	v_add_u32_e32 v1, -1, v1
	v_ashrrev_i32_e32 v39, 6, v32
	v_lshrrev_b32_e32 v4, 1, v1
	v_cmp_lt_u32_e64 s[18:19], s3, v0
	v_and_b32_e32 v0, 0xfffffe, v3
	v_cmp_lt_u32_e64 s[20:21], 1, v1
	v_and_b32_e32 v1, 2, v1
	s_movk_i32 s0, 0x400
	v_lshlrev_b32_e32 v51, 3, v39
	v_lshl_add_u32 v99, v6, 4, 0
	v_and_b32_e32 v38, 15, v32
	s_add_u32 s42, s70, 0xfef9000
	v_add_u32_e32 v4, 1, v4
	v_lshl_add_u32 v102, v0, 9, v32
	v_cmp_eq_u32_e64 s[22:23], 0, v1
	v_cmp_ne_u32_e64 s[24:25], v3, v0
	v_ashrrev_i32_e32 v1, 31, v32
	v_mov_b32_e32 v0, v32
	v_cmp_gt_i32_e64 s[0:1], s0, v32
	v_add_u32_e32 v100, 0x4000, v99
	v_cmp_gt_u32_e64 s[16:17], 16, v6
	v_lshl_add_u32 v101, v38, 12, 0
	s_addc_u32 s43, s71, 0
	v_add_u32_e32 v33, 0x200, v32
	v_and_b32_e32 v103, -2, v4
	v_lshl_add_u32 v104, v32, 2, 0
	v_lshlrev_b64 v[46:47], 2, v[0:1]
	s_and_b32 s93, s2, 7
	s_lshl_b32 s93, s93, 5
	s_lshr_b32 s94, s2, 3
	s_add_u32 s93, s93, s94
	v_lshl_add_u32 v105, s93, 6, v51
	s_lshl_b32 s26, s72, 6
	s_mov_b32 s27, 0x8040
	s_movk_i32 s33, 0x5000
	v_lshlrev_b32_e32 v48, 2, v2
	s_mov_b32 s46, 0x3a800000
	s_mov_b32 s34, 0x800000
	s_mov_b32 s35, 0xbfb8aa3b
	s_mov_b32 s47, 0xb2a5705f
	s_mov_b32 s53, 0x42ce8ed0
	s_mov_b32 s75, 0xc2b17218
	s_mov_b32 s77, 0x7f800000
	s_mov_b32 s79, 0x3f2aaaab
	s_mov_b32 s52, 0x3e9b6dac
	s_mov_b32 s74, 0x3f2aaada
	s_mov_b32 s76, 0x3f317218
	s_mov_b32 s78, 0xb102e308
	s_mov_b32 s92, 0x33800000
	v_mov_b32_e32 v106, 2
	v_mov_b32_e32 v50, 0x358637bd
	v_mov_b32_e32 v107, 0x7f800000
	v_mov_b32_e32 v52, 0x3ecc95a3
	v_readlane_b32 s54, v254, 8
	v_readlane_b32 s55, v254, 9
	v_readlane_b32 s56, v254, 10
	v_readlane_b32 s57, v254, 11
	v_readlane_b32 s58, v254, 12
	v_readlane_b32 s59, v254, 13
	v_readlane_b32 s60, v254, 14
	v_readlane_b32 s61, v254, 15
	v_readlane_b32 s62, v254, 16
	v_readlane_b32 s63, v254, 17
	v_readlane_b32 s64, v254, 18
	v_readlane_b32 s65, v254, 19
	v_readlane_b32 s66, v254, 20
	v_readlane_b32 s67, v254, 21
	s_branch .LBB0_90

; __device__ __forceinline__ unsigned xb_add(unsigned* p, unsigned v) { return __hip_atomic_fetch_add(p, v, __ATOMIC_RELAXED, __HIP_MEMORY_SCOPE_AGENT); }
; __device__ void phase1(const Params& p, LAS unsigned char* lds) {
;     ...
;         __syncthreads();
;     }
; }
; __device__ __forceinline__ void xcd_barrier(const XcdBarrier& b) {
;     asm volatile("s_waitcnt vmcnt(0)" ::: "memory");
;     __syncthreads();
;     if (threadIdx.x == 0) {
;         unsigned* bar = b.bar;
;         __builtin_amdgcn_s_waitcnt(0);
;         unsigned nloc = b.st[0], nx = b.st[1];
;         if (nloc == 0u) { xcd_barrier_complete(bar, b.x, nloc, nx); b.st[0] = nloc; b.st[1] = nx; }
;         const unsigned old = xb_add(&bar[XB_XSUB(b.x)], 1u);
.LBB0_113:
	s_waitcnt vmcnt(0)
	s_barrier
	v_cmp_eq_u32_e32 vcc, 0, v224
	s_and_saveexec_b64 s[4:5], vcc
	s_cbranch_execz .Lpa1_skip
	v_readlane_b32 s6, v254, 5
	s_lshl_b32 s7, s6, 2
	s_lshl_b32 s7, 1, s7
	s_cmp_lt_u32 s6, 8
	s_cselect_b32 s7, s7, 0
	s_and_b32 s8, s2, 7
	s_lshl_b32 s8, s8, 3
	s_lshr_b32 s9, s2, 5
	s_add_u32 s8, s8, s9
	s_lshl_b32 s8, s8, 8
	s_add_u32 s8, s8, 0xff84040
	s_add_u32 s8, s70, s8
	s_addc_u32 s9, s71, 0
	v_mov_b32_e32 v0, 0
	v_mov_b32_e32 v1, s7
	global_atomic_add v0, v1, s[8:9]
.Lpa1_skip:
	s_or_b64 exec, exec, s[4:5]
	s_mov_b64 s[0:1], exec
	v_readlane_b32 s4, v254, 1
	v_readlane_b32 s5, v254, 2
	s_and_b64 s[4:5], s[0:1], s[4:5]
	s_mov_b64 exec, s[4:5]
	s_cbranch_execz .LBB0_165
	s_add_i32 s3, 0, 0x25ff0
	v_mov_b32_e32 v0, s3
	s_waitcnt vmcnt(0) expcnt(0) lgkmcnt(0)
	ds_read_b32 v2, v0
	s_add_i32 s3, 0, 0x25ff4
	v_mov_b32_e32 v0, s3
	ds_read_b32 v0, v0
	s_waitcnt lgkmcnt(1)
	v_cmp_ne_u32_e32 vcc, 0, v2
	s_cbranch_vccnz .LBB0_129
	s_add_u32 s4, s70, 0xff80200
	s_addc_u32 s5, s71, 0
	s_add_u32 s6, s70, 0xff80400
	s_addc_u32 s7, s71, 0
	s_add_u32 s8, s70, 0xff80500
	s_addc_u32 s9, s71, 0
	s_add_u32 s10, s70, 0xff80600
	s_addc_u32 s11, s71, 0
	s_add_u32 s12, s70, 0xff80700
	s_addc_u32 s13, s71, 0
	s_add_u32 s14, s70, 0xff80800
	s_addc_u32 s15, s71, 0
	s_add_u32 s16, s70, 0xff80900
	s_addc_u32 s17, s71, 0
	s_add_u32 s18, s70, 0xff80a00
	s_addc_u32 s19, s71, 0
	s_add_u32 s20, s70, 0xff80b00
	s_addc_u32 s21, s71, 0
	s_add_u32 s22, s70, 0xff80c00
	s_addc_u32 s23, s71, 0
	s_add_u32 s24, s70, 0xff80d00
	s_addc_u32 s25, s71, 0
	s_add_u32 s28, s70, 0xff80e00
	s_addc_u32 s29, s71, 0
	s_add_u32 s30, s70, 0xff80f00
	s_addc_u32 s31, s71, 0
	s_add_u32 s40, s70, 0xff81000
	s_addc_u32 s41, s71, 0
	s_add_u32 s42, s70, 0xff81100
	s_addc_u32 s43, s71, 0
	s_add_u32 s44, s70, 0xff81200
	v_readlane_b32 s3, v254, 0
	s_addc_u32 s45, s71, 0
	s_mul_i32 s3, s73, s3
	s_add_u32 s46, s70, 0xff81300
	s_mul_i32 s3, s3, s72
	s_addc_u32 s47, s71, 0
	s_mov_b32 s26, 1
	v_mov_b32_e32 v16, 0
	s_branch .LBB0_117

; __device__ __forceinline__ unsigned xb_ld(unsigned* p)              { return __hip_atomic_load(p, __ATOMIC_RELAXED, __HIP_MEMORY_SCOPE_AGENT); }
; __device__ __forceinline__ unsigned xb_add(unsigned* p, unsigned v) { return __hip_atomic_fetch_add(p, v, __ATOMIC_RELAXED, __HIP_MEMORY_SCOPE_AGENT); }
; #define XB_SPIN(cond, bar) do { unsigned _sp = 0; while (cond) { __builtin_amdgcn_s_sleep(1); \
;     if ((++_sp & 255u) == 0u) { if (xb_ld(&(bar)[XB_TMO])) break; if (_sp > XB_SPIN_CAP) { atomicAdd(&(bar)[XB_TMO], 1u); break; } } } } while (0)
; __device__ __forceinline__ void xcd_barrier(const XcdBarrier& b) {
;     ...
;             const unsigned og = xb_add(&bar[XB_TOP], 1u);
;             const unsigned tg = og / nx;
;             if (og + 1u == (tg + 1u) * nx) xb_add(&bar[XB_TOPGEN], 1u);
;             else XB_SPIN(xb_ld(&bar[XB_TOPGEN]) == tg, bar);
;             __builtin_amdgcn_fence(__ATOMIC_ACQUIRE, "agent");
;             xb_add(&bar[XB_XGEN(b.x)], 1u);
;             asm volatile("s_waitcnt vmcnt(0)" ::: "memory");
;         } else {
;             XB_SPIN(xb_ld(&bar[XB_XGEN(b.x)]) == gen, bar);
;             __builtin_amdgcn_fence(__ATOMIC_ACQUIRE, "agent");
;             asm volatile("s_waitcnt vmcnt(0)" ::: "memory");
.LBB0_165:
	s_or_b64 exec, exec, s[0:1]
	s_waitcnt lgkmcnt(0)
	v_mov_b32_e32 v0, v224
	v_mov_b32_e32 v14, v224
	v_cmp_eq_u32_e32 vcc, 0, v224
	s_and_saveexec_b64 s[44:45], vcc
	s_cbranch_execz .Lgb1_done
	s_add_u32 s40, s70, 0xff83500
	s_addc_u32 s41, s71, 0
	s_add_u32 s52, s70, 0xff83d00
	s_addc_u32 s53, s71, 0
	s_and_b32 s46, s2, 7
	s_lshl_b32 s46, s46, 3
	s_lshr_b32 s47, s2, 5
	s_add_u32 s46, s46, s47
	s_lshl_b32 s46, s46, 8
	s_add_u32 s46, s46, 0xff84040
	s_add_u32 s46, s70, s46
	s_addc_u32 s47, s71, 0
	v_readlane_b32 s48, v254, 5
	s_mov_b32 s50, 4
	s_cmp_lt_u32 s48, 8
	s_cselect_b32 s50, s50, 16
	s_lshl_b32 s48, s48, 2
	s_mov_b32 s42, 0x8000
	v_mov_b32_e32 v250, 0
.Lgb1_spin:
	global_load_dword v251, v250, s[46:47] sc1
	global_load_dword v252, v250, s[40:41] sc1
	global_load_dword v253, v250, s[52:53] sc1
	s_waitcnt vmcnt(0)
	v_readfirstlane_b32 s43, v251
	v_readfirstlane_b32 s49, v252
	v_readfirstlane_b32 s51, v253
	s_cmp_ge_u32 s49, 1
	s_cbranch_scc1 .Lgb1_ok
	s_lshr_b32 s43, s43, s48
	s_and_b32 s43, s43, 15
	s_cmp_lt_u32 s43, s50
	s_cbranch_scc1 .Lgb1_again
	s_cmp_ge_u32 s51, 0x100
	s_cbranch_scc1 .Lgb1_ok
.Lgb1_again:
	s_sleep 1
	s_sub_u32 s42, s42, 1
	s_cmp_lg_u32 s42, 0
	s_cbranch_scc1 .Lgb1_spin

; __device__ __forceinline__ int opaque_tid() { int t = (int)threadIdx.x; asm volatile("" : "+v"(t)); return t; }
; #define PG8_STAGE(bufoff, gbase, voff) do { _Pragma("unroll") for (int _i = 0; _i < 2; ++_i) \
;         __builtin_amdgcn_global_load_lds((const unsigned*)((const char*)(gbase) + (voff)[_i]), (LAS unsigned*)(lds + (bufoff) + ldsw + _i * 8192), 16, 0, 0); } while (0)
; #define PG8_WAIT_V(n) asm volatile("s_waitcnt vmcnt(" #n ")" ::: "memory")
; #define PG8_BAR __builtin_amdgcn_s_barrier()
; template <class Epi, class Sched, bool ZERO>
; __device__ __forceinline__ void gemm_phase_acc(LAS unsigned char* lds, const Gemm g, const Sched& S, const Epi& E, f32x4 (&acc)[2][2][4][2]) {
;     const int tid = opaque_tid(), wid = __builtin_amdgcn_readfirstlane(tid >> 6), lane = tid & 63, wr = wid >> 2, wc = wid & 3, fr = lane & 15, fq = lane >> 4;
;     const int K = g.K, nt = K / BK;
;     unsigned voffA[2], voffB[2];
; #pragma unroll
;     for (int i = 0; i < 2; ++i) { int R, C; stage_rc(tid * 16 + i * 8192, R, C); const int Rb = (R & ~31) + perm32(R & 31);
;         voffA[i] = (unsigned)(R * K + C) * 2u; voffB[i] = (unsigned)(Rb * K + C) * 2u; }
;     const size_t kstep = (size_t)(BK * 2);
;     const size_t hstep = (size_t)HALF * K * 2;
;     const size_t tstep = 2 * hstep;
;     const unsigned ldsw = (unsigned)wid * 1024u;
;     const int aoff = lds_byte(wr * 64 + fr, fq * 8), boff = lds_byte(wc * 32 + fr, fq * 8);
;     ...
;     Unit cur, nxt; int ui = 0;
;     if (!S.next(0, cur)) return;
;     if constexpr (ZERO) {
; #pragma unroll
;     for (int a = 0; a < 2; ++a)
; #pragma unroll
;         for (int b = 0; b < 2; ++b)
; #pragma unroll
;             for (int m = 0; m < 4; ++m)
; #pragma unroll
;                 for (int n = 0; n < 2; ++n) acc[a][b][m][n] = (f32x4){0.f, 0.f, 0.f, 0.f};
;     }
;     bf16x8 At[4][2], B0[2][2], B1[2][2];
;     const char* cA = (const char*)g.A + (size_t)cur.pm * tstep; const char* cB = (const char*)g.Bt + (size_t)cur.pn * tstep;
;     PG8_STAGE(PG8_SB(0, 0), cB, voffB); PG8_STAGE(PG8_SA(0, 0), cA, voffA); PG8_STAGE(PG8_SB(0, 1), cB + hstep, voffB); PG8_STAGE(PG8_SA(0, 1), cA + hstep, voffA);
;     if (wr == 1) PG8_BAR;
;     PG8_WAIT_V(4); PG8_BAR;
;     PG8_STAGE(PG8_SB(1, 0), cB + kstep, voffB); PG8_STAGE(PG8_SA(1, 0), cA + kstep, voffA); PG8_STAGE(PG8_SB(1, 1), cB + hstep + kstep, voffB);
;     PG8_WAIT_V(6); PG8_BAR;
.Lgb1_done:
	s_or_b64 exec, exec, s[44:45]
	s_barrier
	s_mov_b32 s1, 0x1fffe0
	v_ashrrev_i32_e32 v1, 31, v14
	v_lshrrev_b32_e32 v1, 26, v1
	v_add_u32_e32 v1, v14, v1
	v_ashrrev_i32_e32 v8, 6, v1
	v_bfe_i32 v1, v14, 27, 1
	v_lshlrev_b32_e32 v0, 4, v14
	v_lshrrev_b32_e32 v1, 22, v1
	v_add_u32_e32 v1, v0, v1
	v_and_b32_e32 v1, 0xfffffc00, v1
	v_sub_u32_e32 v1, v0, v1
	v_lshrrev_b32_e32 v2, 4, v1
	v_bitop3_b32 v2, v2, v1, 32 bitop3:0x6c
	v_ashrrev_i32_e32 v1, 31, v1
	v_lshrrev_b32_e32 v1, 26, v1
	v_add_u32_e32 v1, v2, v1
	v_ashrrev_i32_e32 v9, 6, v1
	v_lshlrev_b32_e32 v3, 3, v8
	s_waitcnt vmcnt(1)
	v_mul_i32_i24_e32 v4, 64, v9
	v_and_b32_e32 v3, -16, v3
	v_sub_u32_e32 v2, v2, v4
	v_mov_b32_e32 v4, 1
	v_add_u32_e32 v1, v9, v3
	v_lshlrev_b32_e32 v3, 5, v8
	v_ashrrev_i16_sdwa v2, v4, sext(v2) dst_sel:DWORD dst_unused:UNUSED_PAD src0_sel:DWORD src1_sel:BYTE_0
	v_and_b32_e32 v3, 32, v3
	v_bfe_i32 v10, v2, 0, 16
	v_and_b32_e32 v6, 3, v9
	v_add_lshl_u32 v3, v3, v10, 1
	v_add_u32_e32 v0, 0x2000, v0
	v_lshlrev_b32_e32 v2, 1, v1
	v_lshrrev_b32_e32 v5, 2, v1
	v_and_or_b32 v6, v1, s1, v6
	v_lshl_add_u32 v128, v1, 11, v3
	v_ashrrev_i32_e32 v1, 31, v0
	v_lshrrev_b32_e32 v1, 22, v1
	v_add_u32_e32 v1, v0, v1
	v_ashrrev_i32_e32 v11, 10, v1
	v_mul_i32_i24_e32 v1, 0x400, v11
	v_sub_u32_e32 v0, v0, v1
	v_and_b32_e32 v2, 24, v2
	v_and_b32_e32 v5, 4, v5
	v_lshrrev_b32_e32 v1, 4, v0
	v_or3_b32 v2, v6, v5, v2
	v_bitop3_b32 v0, v1, v0, 32 bitop3:0x6c
	v_lshl_add_u32 v130, v2, 11, v3
	v_ashrrev_i32_e32 v2, 31, v0
	v_lshrrev_b32_e32 v2, 26, v2
	v_add_u32_e32 v2, v0, v2
	s_lshl_b32 s3, s2, 3
	v_lshlrev_b32_e32 v1, 3, v11
	v_ashrrev_i32_e32 v12, 6, v2
	v_and_b32_e32 v2, 0xc0, v2
	s_ashr_i32 s6, s2, 5
	s_and_b32 s3, s3, 56
	v_readfirstlane_b32 s41, v14
	v_and_b32_e32 v1, -16, v1
	v_sub_u32_e32 v0, v0, v2
	s_bfe_u32 s34, s2, 0x20003
	s_mov_b32 s4, s6
	s_add_i32 s18, s3, s6
	s_ashr_i32 s0, s41, 6
	v_add_u32_e32 v1, v12, v1
	v_ashrrev_i16_sdwa v0, v4, sext(v0) dst_sel:DWORD dst_unused:UNUSED_PAD src0_sel:DWORD src1_sel:BYTE_0
	v_and_b32_e32 v4, 3, v12
	v_writelane_b32 v254, s4, 24
	s_or_b32 s6, s34, 0x48
	s_ashr_i32 s19, s18, 31
	v_and_or_b32 v4, v1, s1, v4
	s_ashr_i32 s1, s41, 8
	s_lshl_b32 s26, s0, 10
	v_writelane_b32 v254, s5, 25
	s_lshl_b64 s[4:5], s[18:19], 19
	s_lshl_b32 s3, s6, 19
	s_add_u32 s14, s70, s3
	v_lshlrev_b32_e32 v3, 5, v11
	v_bfe_i32 v13, v0, 0, 16
	v_lshlrev_b32_e32 v0, 1, v1
	v_lshrrev_b32_e32 v2, 2, v1
	s_addc_u32 s15, s71, 0
	s_add_i32 s24, s26, 0
	v_and_b32_e32 v3, 32, v3
	v_and_b32_e32 v0, 24, v0
	v_and_b32_e32 v2, 4, v2
	s_add_i32 m0, s24, 0x10000
	v_or3_b32 v0, v4, v2, v0
	v_add_lshl_u32 v2, v3, v13, 1
	global_load_lds_dwordx4 v130, s[14:15]
	s_add_i32 m0, s24, 0x12000
	v_lshl_add_u32 v134, v0, 11, v2
	s_add_u32 s20, s70, s4
	global_load_lds_dwordx4 v134, s[14:15]
	v_writelane_b32 v254, s4, 26
	s_addc_u32 s21, s71, s5
	s_mov_b32 m0, s24
	s_add_i32 s25, s24, 0x2000
	v_lshl_add_u32 v132, v1, 11, v2
	v_writelane_b32 v254, s5, 27
	global_load_lds_dwordx4 v128, s[20:21]
	s_mov_b32 m0, s25
	s_add_u32 s4, s14, 0x40000
	global_load_lds_dwordx4 v132, s[20:21]
	s_addc_u32 s5, s15, 0
	s_add_i32 m0, s24, 0x14000
	v_mov_b32_e32 v137, 0
	global_load_lds_dwordx4 v130, s[4:5]
	s_add_i32 m0, s24, 0x16000
	v_mov_b32_e32 v131, v137
	global_load_lds_dwordx4 v134, s[4:5]
	s_add_u32 s4, s20, 0x40000
	s_addc_u32 s5, s21, 0
	s_add_i32 s28, s24, 0x4000
	s_mov_b32 m0, s28
	s_add_i32 s29, s24, 0x6000
	global_load_lds_dwordx4 v128, s[4:5]
	s_mov_b32 m0, s29
	v_writelane_b32 v254, s4, 28
	v_mov_b32_e32 v135, v137
	v_mov_b32_e32 v129, v137
	v_mov_b32_e32 v133, v137
	s_mov_b32 s9, 0
	v_lshl_add_u64 v[6:7], s[14:15], 0, v[130:131]
	global_load_lds_dwordx4 v132, s[4:5]
	v_lshl_add_u64 v[4:5], s[14:15], 0, v[134:135]
	v_lshl_add_u64 v[2:3], s[20:21], 0, v[128:129]
	s_cmp_lg_u32 s1, 1
	v_lshl_add_u64 v[0:1], s[20:21], 0, v[132:133]
	v_writelane_b32 v254, s5, 29
	s_cbranch_scc1 .LBB0_167
	s_barrier

; __device__ __forceinline__ unsigned xb_ld(unsigned* p)              { return __hip_atomic_load(p, __ATOMIC_RELAXED, __HIP_MEMORY_SCOPE_AGENT); }
; __device__ __forceinline__ unsigned xb_add(unsigned* p, unsigned v) { return __hip_atomic_fetch_add(p, v, __ATOMIC_RELAXED, __HIP_MEMORY_SCOPE_AGENT); }
; #define XB_SPIN(cond, bar) do { unsigned _sp = 0; while (cond) { __builtin_amdgcn_s_sleep(1); \
;     if ((++_sp & 255u) == 0u) { if (xb_ld(&(bar)[XB_TMO])) break; if (_sp > XB_SPIN_CAP) { atomicAdd(&(bar)[XB_TMO], 1u); break; } } } } while (0)
; __device__ __forceinline__ void xcd_barrier(const XcdBarrier& b) {
;     ...
;             else XB_SPIN(xb_ld(&bar[XB_TOPGEN]) == tg, bar);
;             __builtin_amdgcn_fence(__ATOMIC_ACQUIRE, "agent");
;             xb_add(&bar[XB_XGEN(b.x)], 1u);
;             asm volatile("s_waitcnt vmcnt(0)" ::: "memory");
;         } else {
;             XB_SPIN(xb_ld(&bar[XB_XGEN(b.x)]) == gen, bar);
;             __builtin_amdgcn_fence(__ATOMIC_ACQUIRE, "agent");
;             asm volatile("s_waitcnt vmcnt(0)" ::: "memory");
.LBB0_169:
	s_cmp_lg_u32 s59, 2
	s_cbranch_scc1 .Lgb1c_skip
	v_cmp_eq_u32_e64 s[88:89], 0, v224
	s_and_saveexec_b64 s[90:91], s[88:89]
	s_cbranch_execz .Lgb1c_done
	s_add_u32 s88, s70, 0xff83500
	s_addc_u32 s89, s71, 0
	s_mov_b32 s92, 0x8000
	v_mov_b32_e32 v250, 0
.Lgb1c_spin:
	global_load_dword v251, v250, s[88:89] sc1
	s_waitcnt vmcnt(0)
	v_readfirstlane_b32 s93, v251
	s_cmp_ge_u32 s93, 1
	s_cbranch_scc1 .Lgb1c_ok
	s_sleep 1
	s_sub_u32 s92, s92, 1
	s_cmp_lg_u32 s92, 0
	s_cbranch_scc1 .Lgb1c_spin

; __device__ __forceinline__ void xcd_barrier(const XcdBarrier& b) {
;     ...
;             __builtin_amdgcn_fence(__ATOMIC_ACQUIRE, "agent");
;             asm volatile("s_waitcnt vmcnt(0)" ::: "memory");
;         }
;     }
;     __syncthreads();
.Lgb1c_done:
	s_or_b64 exec, exec, s[90:91]
